# compressed-block phase: no register-bank rotation at all (selection loop unrolled, head loop picks the bank by scalar branch) and dead 64-bit pointer increments removed
# speedup vs baseline: 1.0011x; 1.0011x over previous
; __device__ __forceinline__ int crow(int r, int hi) { return (r & 3) + 8 * (r >> 2) + 4 * hi; }
; __device__ __forceinline__ void cmp_phase(LAS unsigned char* lds, const bf16_t* __restrict__ P, const bf16_t* __restrict__ Kc, const bf16_t* __restrict__ Vc,
;                                           bf16_t* __restrict__ ocmp, unsigned long long* __restrict__ mask, int G, const int wave0) {
;     ...
;                     CMP_QK(c)
;                     const float m_h = mi[(hh * 32 + r32) * 2], i_h = mi[(hh * 32 + r32) * 2 + 1];
;                     if (16 * (64 * c + 63) + 31 > tw0) {
; #pragma unroll
;                         for (int r = 0; r < 16; ++r) {
;                             const int nc = 64 * c + crow(r, hi);
;                             p0[r] = (16 * nc + 31 <= tq) ? p0[r] : -INFINITY; p1[r] = (16 * (nc + 32) + 31 <= tq) ? p1[r] : -INFINITY;
;                         }
;                     }
; #pragma unroll
;                     for (int r = 0; r < 16; ++r) { p0[r] = __builtin_amdgcn_exp2f(p0[r] - m_h) * i_h; p1[r] = __builtin_amdgcn_exp2f(p1[r] - m_h) * i_h; }
; #pragma unroll
;                     for (int k = 0; k < 4; ++k) {
;                         A8[k] += p0[4 * k] + 2.0f * (p0[4 * k + 1] + p0[4 * k + 2] + p0[4 * k + 3]); B8[k] += p0[4 * k];
;                         A8[4 + k] += p1[4 * k] + 2.0f * (p1[4 * k + 1] + p1[4 * k + 2] + p1[4 * k + 3]); B8[4 + k] += p1[4 * k];
;                     }
.Lsu0_779:
	s_waitcnt lgkmcnt(0)
	s_nop 9
	v_sub_f32_e32 v1, v1, v90
	v_exp_f32_e32 v96, v1
	v_sub_f32_e32 v1, v18, v90
	v_exp_f32_e32 v18, v1
	v_sub_f32_e32 v1, v2, v90
	v_exp_f32_e32 v2, v1
	v_sub_f32_e32 v1, v19, v90
	v_exp_f32_e32 v100, v1
	v_sub_f32_e32 v1, v3, v90
	v_sub_f32_e32 v3, v21, v90
	v_exp_f32_e32 v95, v3
	v_sub_f32_e32 v3, v5, v90
	v_exp_f32_e32 v97, v3
	v_sub_f32_e32 v3, v22, v90
	v_sub_f32_e32 v5, v8, v90
	v_exp_f32_e32 v19, v3
	v_sub_f32_e32 v3, v6, v90
	v_exp_f32_e32 v6, v5
	v_sub_f32_e32 v5, v25, v90
	v_exp_f32_e32 v8, v5
	v_sub_f32_e32 v5, v9, v90
	v_sub_f32_e32 v17, v17, v90
	v_exp_f32_e32 v102, v1
	v_sub_f32_e32 v1, v20, v90
	v_exp_f32_e32 v20, v5
	v_sub_f32_e32 v5, v26, v90
	v_exp_f32_e32 v94, v17
	v_exp_f32_e32 v17, v1
	v_sub_f32_e32 v1, v4, v90
	v_exp_f32_e32 v3, v3
	v_sub_f32_e32 v4, v23, v90
	v_exp_f32_e32 v22, v5
	v_sub_f32_e32 v5, v10, v90
	v_exp_f32_e32 v101, v4
	v_sub_f32_e32 v4, v7, v90
	v_exp_f32_e32 v10, v5
	v_sub_f32_e32 v5, v27, v90
	v_exp_f32_e32 v103, v4
	v_sub_f32_e32 v4, v24, v90
	v_exp_f32_e32 v24, v5
	v_sub_f32_e32 v5, v11, v90
	v_sub_f32_e32 v11, v13, v90
	v_sub_f32_e32 v0, v0, v90
	v_exp_f32_e32 v21, v11
	v_sub_f32_e32 v11, v30, v90
	v_exp_f32_e32 v0, v0
	v_exp_f32_e32 v1, v1
	v_sub_f32_e32 v9, v29, v90
	v_exp_f32_e32 v23, v11
	v_pk_mul_f32 v[2:3], v[90:91], v[2:3] op_sel:[1,0]
	v_sub_f32_e32 v7, v12, v90
	v_exp_f32_e32 v9, v9
	v_sub_f32_e32 v12, v31, v90
	v_pk_fma_f32 v[2:3], v[90:91], v[96:97], v[2:3] op_sel:[1,0,0]
	v_exp_f32_e32 v25, v12
	v_pk_fma_f32 v[2:3], v[90:91], v[102:103], v[2:3] op_sel:[1,0,0]
	v_exp_f32_e32 v26, v5
	v_sub_f32_e32 v5, v28, v90
	v_pk_add_f32 v[2:3], v[2:3], v[2:3]
	v_exp_f32_e32 v4, v4
	v_exp_f32_e32 v5, v5
	v_sub_f32_e32 v11, v14, v90
	v_pk_fma_f32 v[2:3], v[90:91], v[0:1], v[2:3] op_sel:[1,0,0]
	v_pk_fma_f32 v[70:71], v[90:91], v[0:1], v[70:71] op_sel:[1,0,0]
	v_pk_mul_f32 v[0:1], v[90:91], v[22:23] op_sel:[1,0]
	v_exp_f32_e32 v11, v11
	v_pk_fma_f32 v[0:1], v[90:91], v[8:9], v[0:1] op_sel:[1,0,0]
	v_sub_f32_e32 v12, v15, v90
	v_pk_fma_f32 v[0:1], v[90:91], v[24:25], v[0:1] op_sel:[1,0,0]
	v_exp_f32_e32 v27, v12
	v_pk_add_f32 v[0:1], v[0:1], v[0:1]
	v_sub_f32_e32 v16, v16, v90
	v_pk_fma_f32 v[0:1], v[90:91], v[4:5], v[0:1] op_sel:[1,0,0]
	v_exp_f32_e32 v16, v16
	v_exp_f32_e32 v7, v7
	v_pk_mul_f32 v[12:13], v[90:91], v[18:19] op_sel:[1,0]
	v_pk_add_f32 v[84:85], v[84:85], v[0:1]
	v_pk_mul_f32 v[0:1], v[90:91], v[10:11] op_sel:[1,0]
	v_pk_fma_f32 v[12:13], v[90:91], v[94:95], v[12:13] op_sel:[1,0,0]
	v_pk_fma_f32 v[0:1], v[90:91], v[20:21], v[0:1] op_sel:[1,0,0]
	v_pk_fma_f32 v[12:13], v[90:91], v[100:101], v[12:13] op_sel:[1,0,0]
	v_pk_fma_f32 v[0:1], v[90:91], v[26:27], v[0:1] op_sel:[1,0,0]
	v_pk_add_f32 v[12:13], v[12:13], v[12:13]
	v_pk_add_f32 v[0:1], v[0:1], v[0:1]
	v_pk_fma_f32 v[12:13], v[90:91], v[16:17], v[12:13] op_sel:[1,0,0]
	v_pk_fma_f32 v[0:1], v[90:91], v[6:7], v[0:1] op_sel:[1,0,0]
	s_addk_i32 s74, 0x100
	v_pk_add_f32 v[86:87], v[86:87], v[12:13]
	v_pk_fma_f32 v[74:75], v[90:91], v[16:17], v[74:75] op_sel:[1,0,0]
	v_pk_add_f32 v[78:79], v[78:79], v[2:3]
	v_pk_fma_f32 v[72:73], v[90:91], v[4:5], v[72:73] op_sel:[1,0,0]
	v_pk_add_f32 v[76:77], v[76:77], v[0:1]
	v_pk_fma_f32 v[68:69], v[90:91], v[6:7], v[68:69] op_sel:[1,0,0]
.Lsu1_780:
	v_add_u32_e32 v90, s74, v92
	v_add_u32_e32 v90, 0x21400, v90
	ds_read_b64 v[90:91], v90
	s_andn2_b64 vcc, exec, s[84:85]
	s_waitcnt lgkmcnt(8)
	v_mfma_f32_32x32x16_bf16 v[16:31], v[32:35], v[200:203], 0
	s_waitcnt lgkmcnt(6)
	v_mfma_f32_32x32x16_bf16 v[0:15], v[40:43], v[200:203], 0
	v_mfma_f32_32x32x16_bf16 v[16:31], v[36:39], v[204:207], v[16:31]
	s_waitcnt lgkmcnt(5)
	v_mfma_f32_32x32x16_bf16 v[0:15], v[44:47], v[204:207], v[0:15]
	s_waitcnt lgkmcnt(4)
	v_mfma_f32_32x32x16_bf16 v[16:31], v[48:51], v[208:211], v[16:31]
	s_waitcnt lgkmcnt(2)
	v_mfma_f32_32x32x16_bf16 v[0:15], v[56:59], v[208:211], v[0:15]
	v_mfma_f32_32x32x16_bf16 v[16:31], v[52:55], v[216:219], v[16:31]
	s_waitcnt lgkmcnt(1)
	v_mfma_f32_32x32x16_bf16 v[0:15], v[60:63], v[216:219], v[0:15]
	s_cbranch_vccnz .Lsu1_779
	s_nop 8
	v_cndmask_b32_e64 v16, v16, v249, s[4:5]
	s_nop 0
	v_cndmask_b32_e64 v0, v0, v249, s[6:7]
	v_cndmask_b32_e64 v17, v17, v249, s[8:9]
	v_cndmask_b32_e64 v1, v1, v249, s[10:11]
	v_cndmask_b32_e64 v18, v18, v249, s[12:13]
	v_cndmask_b32_e64 v2, v2, v249, s[14:15]
	v_cndmask_b32_e64 v19, v19, v249, s[16:17]
	v_cndmask_b32_e64 v3, v3, v249, s[18:19]
	v_cndmask_b32_e64 v20, v20, v249, s[20:21]
	v_cndmask_b32_e64 v4, v4, v249, s[22:23]
	v_cndmask_b32_e64 v21, v21, v249, s[24:25]
	v_cndmask_b32_e64 v5, v5, v249, s[26:27]
	v_cndmask_b32_e64 v22, v22, v249, s[28:29]
	v_cndmask_b32_e64 v6, v6, v249, s[30:31]
	v_cndmask_b32_e64 v23, v23, v249, s[34:35]
	v_cndmask_b32_e64 v7, v7, v249, s[36:37]
	v_cndmask_b32_e64 v24, v24, v249, s[38:39]
	v_cndmask_b32_e64 v8, v8, v249, s[40:41]
	v_cndmask_b32_e64 v25, v25, v249, s[42:43]
	v_cndmask_b32_e64 v9, v9, v249, s[44:45]
	v_cndmask_b32_e64 v26, v26, v249, s[46:47]
	v_cndmask_b32_e64 v10, v10, v249, s[48:49]
	v_cndmask_b32_e64 v27, v27, v249, s[50:51]
	v_cndmask_b32_e64 v11, v11, v249, s[52:53]
	v_cndmask_b32_e64 v28, v28, v249, s[54:55]
	v_cndmask_b32_e64 v12, v12, v249, s[56:57]
	v_cndmask_b32_e64 v29, v29, v249, s[58:59]
	v_cndmask_b32_e64 v13, v13, v249, s[60:61]
	v_cndmask_b32_e64 v30, v30, v249, s[62:63]
	v_cndmask_b32_e64 v14, v14, v249, s[64:65]
	v_cndmask_b32_e64 v31, v31, v249, s[66:67]
	v_cndmask_b32_e64 v15, v15, v249, s[68:69]
; __device__ __forceinline__ int crow(int r, int hi) { return (r & 3) + 8 * (r >> 2) + 4 * hi; }
; __device__ __forceinline__ void cmp_phase(LAS unsigned char* lds, const bf16_t* __restrict__ P, const bf16_t* __restrict__ Kc, const bf16_t* __restrict__ Vc,
;                                           bf16_t* __restrict__ ocmp, unsigned long long* __restrict__ mask, int G, const int wave0) {
;     ...
;                     CMP_QK(c)
;                     const float m_h = mi[(hh * 32 + r32) * 2], i_h = mi[(hh * 32 + r32) * 2 + 1];
;                     if (16 * (64 * c + 63) + 31 > tw0) {
; #pragma unroll
;                         for (int r = 0; r < 16; ++r) {
;                             const int nc = 64 * c + crow(r, hi);
;                             p0[r] = (16 * nc + 31 <= tq) ? p0[r] : -INFINITY; p1[r] = (16 * (nc + 32) + 31 <= tq) ? p1[r] : -INFINITY;
;                         }
;                     }
; #pragma unroll
;                     for (int r = 0; r < 16; ++r) { p0[r] = __builtin_amdgcn_exp2f(p0[r] - m_h) * i_h; p1[r] = __builtin_amdgcn_exp2f(p1[r] - m_h) * i_h; }
; #pragma unroll
;                     for (int k = 0; k < 4; ++k) {
;                         A8[k] += p0[4 * k] + 2.0f * (p0[4 * k + 1] + p0[4 * k + 2] + p0[4 * k + 3]); B8[k] += p0[4 * k];
;                         A8[4 + k] += p1[4 * k] + 2.0f * (p1[4 * k + 1] + p1[4 * k + 2] + p1[4 * k + 3]); B8[4 + k] += p1[4 * k];
;                     }
.Lsu1_779:
	s_waitcnt lgkmcnt(0)
	s_nop 9
	v_sub_f32_e32 v1, v1, v90
	v_exp_f32_e32 v96, v1
	v_sub_f32_e32 v1, v18, v90
	v_exp_f32_e32 v18, v1
	v_sub_f32_e32 v1, v2, v90
	v_exp_f32_e32 v2, v1
	v_sub_f32_e32 v1, v19, v90
	v_exp_f32_e32 v100, v1
	v_sub_f32_e32 v1, v3, v90
	v_sub_f32_e32 v3, v21, v90
	v_exp_f32_e32 v95, v3
	v_sub_f32_e32 v3, v5, v90
	v_exp_f32_e32 v97, v3
	v_sub_f32_e32 v3, v22, v90
	v_sub_f32_e32 v5, v8, v90
	v_exp_f32_e32 v19, v3
	v_sub_f32_e32 v3, v6, v90
	v_exp_f32_e32 v6, v5
	v_sub_f32_e32 v5, v25, v90
	v_exp_f32_e32 v8, v5
	v_sub_f32_e32 v5, v9, v90
	v_sub_f32_e32 v17, v17, v90
	v_exp_f32_e32 v102, v1
	v_sub_f32_e32 v1, v20, v90
	v_exp_f32_e32 v20, v5
	v_sub_f32_e32 v5, v26, v90
	v_exp_f32_e32 v94, v17
	v_exp_f32_e32 v17, v1
	v_sub_f32_e32 v1, v4, v90
	v_exp_f32_e32 v3, v3
	v_sub_f32_e32 v4, v23, v90
	v_exp_f32_e32 v22, v5
	v_sub_f32_e32 v5, v10, v90
	v_exp_f32_e32 v101, v4
	v_sub_f32_e32 v4, v7, v90
	v_exp_f32_e32 v10, v5
	v_sub_f32_e32 v5, v27, v90
	v_exp_f32_e32 v103, v4
	v_sub_f32_e32 v4, v24, v90
	v_exp_f32_e32 v24, v5
	v_sub_f32_e32 v5, v11, v90
	v_sub_f32_e32 v11, v13, v90
	v_sub_f32_e32 v0, v0, v90
	v_exp_f32_e32 v21, v11
	v_sub_f32_e32 v11, v30, v90
	v_exp_f32_e32 v0, v0
	v_exp_f32_e32 v1, v1
	v_sub_f32_e32 v9, v29, v90
	v_exp_f32_e32 v23, v11
	v_pk_mul_f32 v[2:3], v[90:91], v[2:3] op_sel:[1,0]
	v_sub_f32_e32 v7, v12, v90
	v_exp_f32_e32 v9, v9
	v_sub_f32_e32 v12, v31, v90
	v_pk_fma_f32 v[2:3], v[90:91], v[96:97], v[2:3] op_sel:[1,0,0]
	v_exp_f32_e32 v25, v12
	v_pk_fma_f32 v[2:3], v[90:91], v[102:103], v[2:3] op_sel:[1,0,0]
	v_exp_f32_e32 v26, v5
	v_sub_f32_e32 v5, v28, v90
	v_pk_add_f32 v[2:3], v[2:3], v[2:3]
	v_exp_f32_e32 v4, v4
	v_exp_f32_e32 v5, v5
	v_sub_f32_e32 v11, v14, v90
	v_pk_fma_f32 v[2:3], v[90:91], v[0:1], v[2:3] op_sel:[1,0,0]
	v_pk_fma_f32 v[70:71], v[90:91], v[0:1], v[70:71] op_sel:[1,0,0]
	v_pk_mul_f32 v[0:1], v[90:91], v[22:23] op_sel:[1,0]
	v_exp_f32_e32 v11, v11
	v_pk_fma_f32 v[0:1], v[90:91], v[8:9], v[0:1] op_sel:[1,0,0]
	v_sub_f32_e32 v12, v15, v90
	v_pk_fma_f32 v[0:1], v[90:91], v[24:25], v[0:1] op_sel:[1,0,0]
	v_exp_f32_e32 v27, v12
	v_pk_add_f32 v[0:1], v[0:1], v[0:1]
	v_sub_f32_e32 v16, v16, v90
	v_pk_fma_f32 v[0:1], v[90:91], v[4:5], v[0:1] op_sel:[1,0,0]
	v_exp_f32_e32 v16, v16
	v_exp_f32_e32 v7, v7
	v_pk_mul_f32 v[12:13], v[90:91], v[18:19] op_sel:[1,0]
	v_pk_add_f32 v[84:85], v[84:85], v[0:1]
	v_pk_mul_f32 v[0:1], v[90:91], v[10:11] op_sel:[1,0]
	v_pk_fma_f32 v[12:13], v[90:91], v[94:95], v[12:13] op_sel:[1,0,0]
	v_pk_fma_f32 v[0:1], v[90:91], v[20:21], v[0:1] op_sel:[1,0,0]
	v_pk_fma_f32 v[12:13], v[90:91], v[100:101], v[12:13] op_sel:[1,0,0]
	v_pk_fma_f32 v[0:1], v[90:91], v[26:27], v[0:1] op_sel:[1,0,0]
	v_pk_add_f32 v[12:13], v[12:13], v[12:13]
	v_pk_add_f32 v[0:1], v[0:1], v[0:1]
	v_pk_fma_f32 v[12:13], v[90:91], v[16:17], v[12:13] op_sel:[1,0,0]
	v_pk_fma_f32 v[0:1], v[90:91], v[6:7], v[0:1] op_sel:[1,0,0]
	s_addk_i32 s74, 0x100
	v_pk_add_f32 v[86:87], v[86:87], v[12:13]
	v_pk_fma_f32 v[74:75], v[90:91], v[16:17], v[74:75] op_sel:[1,0,0]
	v_pk_add_f32 v[78:79], v[78:79], v[2:3]
	v_pk_fma_f32 v[72:73], v[90:91], v[4:5], v[72:73] op_sel:[1,0,0]
	v_pk_add_f32 v[76:77], v[76:77], v[0:1]
	v_pk_fma_f32 v[68:69], v[90:91], v[6:7], v[68:69] op_sel:[1,0,0]
.Lsu2_780:
	v_add_u32_e32 v90, s74, v92
	v_add_u32_e32 v90, 0x21400, v90
	ds_read_b64 v[90:91], v90
	s_andn2_b64 vcc, exec, s[84:85]
	s_waitcnt lgkmcnt(8)
	v_mfma_f32_32x32x16_bf16 v[16:31], v[32:35], v[220:223], 0
	s_waitcnt lgkmcnt(6)
	v_mfma_f32_32x32x16_bf16 v[0:15], v[40:43], v[220:223], 0
	v_mfma_f32_32x32x16_bf16 v[16:31], v[36:39], v[224:227], v[16:31]
	s_waitcnt lgkmcnt(5)
	v_mfma_f32_32x32x16_bf16 v[0:15], v[44:47], v[224:227], v[0:15]
	s_waitcnt lgkmcnt(4)
	v_mfma_f32_32x32x16_bf16 v[16:31], v[48:51], v[228:231], v[16:31]
	s_waitcnt lgkmcnt(2)
	v_mfma_f32_32x32x16_bf16 v[0:15], v[56:59], v[228:231], v[0:15]
	v_mfma_f32_32x32x16_bf16 v[16:31], v[52:55], v[232:235], v[16:31]
	s_waitcnt lgkmcnt(1)
	v_mfma_f32_32x32x16_bf16 v[0:15], v[60:63], v[232:235], v[0:15]
	s_cbranch_vccnz .Lsu2_779
	s_nop 8
	v_cndmask_b32_e64 v16, v16, v249, s[4:5]
	s_nop 0
	v_cndmask_b32_e64 v0, v0, v249, s[6:7]
	v_cndmask_b32_e64 v17, v17, v249, s[8:9]
	v_cndmask_b32_e64 v1, v1, v249, s[10:11]
	v_cndmask_b32_e64 v18, v18, v249, s[12:13]
	v_cndmask_b32_e64 v2, v2, v249, s[14:15]
	v_cndmask_b32_e64 v19, v19, v249, s[16:17]
	v_cndmask_b32_e64 v3, v3, v249, s[18:19]
	v_cndmask_b32_e64 v20, v20, v249, s[20:21]
	v_cndmask_b32_e64 v4, v4, v249, s[22:23]
	v_cndmask_b32_e64 v21, v21, v249, s[24:25]
	v_cndmask_b32_e64 v5, v5, v249, s[26:27]
	v_cndmask_b32_e64 v22, v22, v249, s[28:29]
	v_cndmask_b32_e64 v6, v6, v249, s[30:31]
	v_cndmask_b32_e64 v23, v23, v249, s[34:35]
	v_cndmask_b32_e64 v7, v7, v249, s[36:37]
	v_cndmask_b32_e64 v24, v24, v249, s[38:39]
	v_cndmask_b32_e64 v8, v8, v249, s[40:41]
	v_cndmask_b32_e64 v25, v25, v249, s[42:43]
	v_cndmask_b32_e64 v9, v9, v249, s[44:45]
	v_cndmask_b32_e64 v26, v26, v249, s[46:47]
	v_cndmask_b32_e64 v10, v10, v249, s[48:49]
	v_cndmask_b32_e64 v27, v27, v249, s[50:51]
	v_cndmask_b32_e64 v11, v11, v249, s[52:53]
	v_cndmask_b32_e64 v28, v28, v249, s[54:55]
	v_cndmask_b32_e64 v12, v12, v249, s[56:57]
	v_cndmask_b32_e64 v29, v29, v249, s[58:59]
	v_cndmask_b32_e64 v13, v13, v249, s[60:61]
	v_cndmask_b32_e64 v30, v30, v249, s[62:63]
	v_cndmask_b32_e64 v14, v14, v249, s[64:65]
	v_cndmask_b32_e64 v31, v31, v249, s[66:67]
	v_cndmask_b32_e64 v15, v15, v249, s[68:69]
; __device__ __forceinline__ int crow(int r, int hi) { return (r & 3) + 8 * (r >> 2) + 4 * hi; }
; __device__ __forceinline__ void cmp_phase(LAS unsigned char* lds, const bf16_t* __restrict__ P, const bf16_t* __restrict__ Kc, const bf16_t* __restrict__ Vc,
;                                           bf16_t* __restrict__ ocmp, unsigned long long* __restrict__ mask, int G, const int wave0) {
;     ...
;                     CMP_QK(c)
;                     const float m_h = mi[(hh * 32 + r32) * 2], i_h = mi[(hh * 32 + r32) * 2 + 1];
;                     if (16 * (64 * c + 63) + 31 > tw0) {
; #pragma unroll
;                         for (int r = 0; r < 16; ++r) {
;                             const int nc = 64 * c + crow(r, hi);
;                             p0[r] = (16 * nc + 31 <= tq) ? p0[r] : -INFINITY; p1[r] = (16 * (nc + 32) + 31 <= tq) ? p1[r] : -INFINITY;
;                         }
;                     }
; #pragma unroll
;                     for (int r = 0; r < 16; ++r) { p0[r] = __builtin_amdgcn_exp2f(p0[r] - m_h) * i_h; p1[r] = __builtin_amdgcn_exp2f(p1[r] - m_h) * i_h; }
; #pragma unroll
;                     for (int k = 0; k < 4; ++k) {
;                         A8[k] += p0[4 * k] + 2.0f * (p0[4 * k + 1] + p0[4 * k + 2] + p0[4 * k + 3]); B8[k] += p0[4 * k];
;                         A8[4 + k] += p1[4 * k] + 2.0f * (p1[4 * k + 1] + p1[4 * k + 2] + p1[4 * k + 3]); B8[4 + k] += p1[4 * k];
;                     }
.Lsu2_779:
	s_waitcnt lgkmcnt(0)
	s_nop 9
	v_sub_f32_e32 v1, v1, v90
	v_exp_f32_e32 v96, v1
	v_sub_f32_e32 v1, v18, v90
	v_exp_f32_e32 v18, v1
	v_sub_f32_e32 v1, v2, v90
	v_exp_f32_e32 v2, v1
	v_sub_f32_e32 v1, v19, v90
	v_exp_f32_e32 v100, v1
	v_sub_f32_e32 v1, v3, v90
	v_sub_f32_e32 v3, v21, v90
	v_exp_f32_e32 v95, v3
	v_sub_f32_e32 v3, v5, v90
	v_exp_f32_e32 v97, v3
	v_sub_f32_e32 v3, v22, v90
	v_sub_f32_e32 v5, v8, v90
	v_exp_f32_e32 v19, v3
	v_sub_f32_e32 v3, v6, v90
	v_exp_f32_e32 v6, v5
	v_sub_f32_e32 v5, v25, v90
	v_exp_f32_e32 v8, v5
	v_sub_f32_e32 v5, v9, v90
	v_sub_f32_e32 v17, v17, v90
	v_exp_f32_e32 v102, v1
	v_sub_f32_e32 v1, v20, v90
	v_exp_f32_e32 v20, v5
	v_sub_f32_e32 v5, v26, v90
	v_exp_f32_e32 v94, v17
	v_exp_f32_e32 v17, v1
	v_sub_f32_e32 v1, v4, v90
	v_exp_f32_e32 v3, v3
	v_sub_f32_e32 v4, v23, v90
	v_exp_f32_e32 v22, v5
	v_sub_f32_e32 v5, v10, v90
	v_exp_f32_e32 v101, v4
	v_sub_f32_e32 v4, v7, v90
	v_exp_f32_e32 v10, v5
	v_sub_f32_e32 v5, v27, v90
	v_exp_f32_e32 v103, v4
	v_sub_f32_e32 v4, v24, v90
	v_exp_f32_e32 v24, v5
	v_sub_f32_e32 v5, v11, v90
	v_sub_f32_e32 v11, v13, v90
	v_sub_f32_e32 v0, v0, v90
	v_exp_f32_e32 v21, v11
	v_sub_f32_e32 v11, v30, v90
	v_exp_f32_e32 v0, v0
	v_exp_f32_e32 v1, v1
	v_sub_f32_e32 v9, v29, v90
	v_exp_f32_e32 v23, v11
	v_pk_mul_f32 v[2:3], v[90:91], v[2:3] op_sel:[1,0]
	v_sub_f32_e32 v7, v12, v90
	v_exp_f32_e32 v9, v9
	v_sub_f32_e32 v12, v31, v90
	v_pk_fma_f32 v[2:3], v[90:91], v[96:97], v[2:3] op_sel:[1,0,0]
	v_exp_f32_e32 v25, v12
	v_pk_fma_f32 v[2:3], v[90:91], v[102:103], v[2:3] op_sel:[1,0,0]
	v_exp_f32_e32 v26, v5
	v_sub_f32_e32 v5, v28, v90
	v_pk_add_f32 v[2:3], v[2:3], v[2:3]
	v_exp_f32_e32 v4, v4
	v_exp_f32_e32 v5, v5
	v_sub_f32_e32 v11, v14, v90
	v_pk_fma_f32 v[2:3], v[90:91], v[0:1], v[2:3] op_sel:[1,0,0]
	v_pk_fma_f32 v[70:71], v[90:91], v[0:1], v[70:71] op_sel:[1,0,0]
	v_pk_mul_f32 v[0:1], v[90:91], v[22:23] op_sel:[1,0]
	v_exp_f32_e32 v11, v11
	v_pk_fma_f32 v[0:1], v[90:91], v[8:9], v[0:1] op_sel:[1,0,0]
	v_sub_f32_e32 v12, v15, v90
	v_pk_fma_f32 v[0:1], v[90:91], v[24:25], v[0:1] op_sel:[1,0,0]
	v_exp_f32_e32 v27, v12
	v_pk_add_f32 v[0:1], v[0:1], v[0:1]
	v_sub_f32_e32 v16, v16, v90
	v_pk_fma_f32 v[0:1], v[90:91], v[4:5], v[0:1] op_sel:[1,0,0]
	v_exp_f32_e32 v16, v16
	v_exp_f32_e32 v7, v7
	v_pk_mul_f32 v[12:13], v[90:91], v[18:19] op_sel:[1,0]
	v_pk_add_f32 v[84:85], v[84:85], v[0:1]
	v_pk_mul_f32 v[0:1], v[90:91], v[10:11] op_sel:[1,0]
	v_pk_fma_f32 v[12:13], v[90:91], v[94:95], v[12:13] op_sel:[1,0,0]
	v_pk_fma_f32 v[0:1], v[90:91], v[20:21], v[0:1] op_sel:[1,0,0]
	v_pk_fma_f32 v[12:13], v[90:91], v[100:101], v[12:13] op_sel:[1,0,0]
	v_pk_fma_f32 v[0:1], v[90:91], v[26:27], v[0:1] op_sel:[1,0,0]
	v_pk_add_f32 v[12:13], v[12:13], v[12:13]
	v_pk_add_f32 v[0:1], v[0:1], v[0:1]
	v_pk_fma_f32 v[12:13], v[90:91], v[16:17], v[12:13] op_sel:[1,0,0]
	v_pk_fma_f32 v[0:1], v[90:91], v[6:7], v[0:1] op_sel:[1,0,0]
	s_addk_i32 s74, 0x100
	v_pk_add_f32 v[86:87], v[86:87], v[12:13]
	v_pk_fma_f32 v[74:75], v[90:91], v[16:17], v[74:75] op_sel:[1,0,0]
	v_pk_add_f32 v[78:79], v[78:79], v[2:3]
	v_pk_fma_f32 v[72:73], v[90:91], v[4:5], v[72:73] op_sel:[1,0,0]
	v_pk_add_f32 v[76:77], v[76:77], v[0:1]
	v_pk_fma_f32 v[68:69], v[90:91], v[6:7], v[68:69] op_sel:[1,0,0]
.Lsu3_780:
	v_add_u32_e32 v90, s74, v92
	v_add_u32_e32 v90, 0x21400, v90
	ds_read_b64 v[90:91], v90
	s_andn2_b64 vcc, exec, s[84:85]
	s_waitcnt lgkmcnt(8)
	v_mfma_f32_32x32x16_bf16 v[16:31], v[32:35], v[130:133], 0
	s_waitcnt lgkmcnt(6)
	v_mfma_f32_32x32x16_bf16 v[0:15], v[40:43], v[130:133], 0
	v_mfma_f32_32x32x16_bf16 v[16:31], v[36:39], v[134:137], v[16:31]
	s_waitcnt lgkmcnt(5)
	v_mfma_f32_32x32x16_bf16 v[0:15], v[44:47], v[134:137], v[0:15]
	s_waitcnt lgkmcnt(4)
	v_mfma_f32_32x32x16_bf16 v[16:31], v[48:51], v[138:141], v[16:31]
	s_waitcnt lgkmcnt(2)
	v_mfma_f32_32x32x16_bf16 v[0:15], v[56:59], v[138:141], v[0:15]
	v_mfma_f32_32x32x16_bf16 v[16:31], v[52:55], v[142:145], v[16:31]
	s_waitcnt lgkmcnt(1)
	v_mfma_f32_32x32x16_bf16 v[0:15], v[60:63], v[142:145], v[0:15]
	s_cbranch_vccnz .Lsu3_779
	s_nop 8
	v_cndmask_b32_e64 v16, v16, v249, s[4:5]
	s_nop 0
	v_cndmask_b32_e64 v0, v0, v249, s[6:7]
	v_cndmask_b32_e64 v17, v17, v249, s[8:9]
	v_cndmask_b32_e64 v1, v1, v249, s[10:11]
	v_cndmask_b32_e64 v18, v18, v249, s[12:13]
	v_cndmask_b32_e64 v2, v2, v249, s[14:15]
	v_cndmask_b32_e64 v19, v19, v249, s[16:17]
	v_cndmask_b32_e64 v3, v3, v249, s[18:19]
	v_cndmask_b32_e64 v20, v20, v249, s[20:21]
	v_cndmask_b32_e64 v4, v4, v249, s[22:23]
	v_cndmask_b32_e64 v21, v21, v249, s[24:25]
	v_cndmask_b32_e64 v5, v5, v249, s[26:27]
	v_cndmask_b32_e64 v22, v22, v249, s[28:29]
	v_cndmask_b32_e64 v6, v6, v249, s[30:31]
	v_cndmask_b32_e64 v23, v23, v249, s[34:35]
	v_cndmask_b32_e64 v7, v7, v249, s[36:37]
	v_cndmask_b32_e64 v24, v24, v249, s[38:39]
	v_cndmask_b32_e64 v8, v8, v249, s[40:41]
	v_cndmask_b32_e64 v25, v25, v249, s[42:43]
	v_cndmask_b32_e64 v9, v9, v249, s[44:45]
	v_cndmask_b32_e64 v26, v26, v249, s[46:47]
	v_cndmask_b32_e64 v10, v10, v249, s[48:49]
	v_cndmask_b32_e64 v27, v27, v249, s[50:51]
	v_cndmask_b32_e64 v11, v11, v249, s[52:53]
	v_cndmask_b32_e64 v28, v28, v249, s[54:55]
	v_cndmask_b32_e64 v12, v12, v249, s[56:57]
	v_cndmask_b32_e64 v29, v29, v249, s[58:59]
	v_cndmask_b32_e64 v13, v13, v249, s[60:61]
	v_cndmask_b32_e64 v30, v30, v249, s[62:63]
	v_cndmask_b32_e64 v14, v14, v249, s[64:65]
	v_cndmask_b32_e64 v31, v31, v249, s[66:67]
	v_cndmask_b32_e64 v15, v15, v249, s[68:69]
; __device__ __forceinline__ void cmp_phase(LAS unsigned char* lds, const bf16_t* __restrict__ P, const bf16_t* __restrict__ Kc, const bf16_t* __restrict__ Vc,
;                                           bf16_t* __restrict__ ocmp, unsigned long long* __restrict__ mask, int G, const int wave0) {
;     ...
; #pragma unroll
;                     for (int r = 0; r < 16; ++r) { p0[r] = __builtin_amdgcn_exp2f(p0[r] - m_h) * i_h; p1[r] = __builtin_amdgcn_exp2f(p1[r] - m_h) * i_h; }
; #pragma unroll
;                     for (int k = 0; k < 4; ++k) {
;                         A8[k] += p0[4 * k] + 2.0f * (p0[4 * k + 1] + p0[4 * k + 2] + p0[4 * k + 3]); B8[k] += p0[4 * k];
;                         A8[4 + k] += p1[4 * k] + 2.0f * (p1[4 * k + 1] + p1[4 * k + 2] + p1[4 * k + 3]); B8[4 + k] += p1[4 * k];
;                     }
.Lsu3_779:
	s_waitcnt lgkmcnt(0)
	s_nop 9
	v_sub_f32_e32 v1, v1, v90
	v_exp_f32_e32 v96, v1
	v_sub_f32_e32 v1, v18, v90
	v_exp_f32_e32 v18, v1
	v_sub_f32_e32 v1, v2, v90
	v_exp_f32_e32 v2, v1
	v_sub_f32_e32 v1, v19, v90
	v_exp_f32_e32 v100, v1
	v_sub_f32_e32 v1, v3, v90
	v_sub_f32_e32 v3, v21, v90
	v_exp_f32_e32 v95, v3
	v_sub_f32_e32 v3, v5, v90
	v_exp_f32_e32 v97, v3
	v_sub_f32_e32 v3, v22, v90
	v_sub_f32_e32 v5, v8, v90
	v_exp_f32_e32 v19, v3
	v_sub_f32_e32 v3, v6, v90
	v_exp_f32_e32 v6, v5
	v_sub_f32_e32 v5, v25, v90
	v_exp_f32_e32 v8, v5
	v_sub_f32_e32 v5, v9, v90
	v_sub_f32_e32 v17, v17, v90
	v_exp_f32_e32 v102, v1
	v_sub_f32_e32 v1, v20, v90
	v_exp_f32_e32 v20, v5
	v_sub_f32_e32 v5, v26, v90
	v_exp_f32_e32 v94, v17
	v_exp_f32_e32 v17, v1
	v_sub_f32_e32 v1, v4, v90
	v_exp_f32_e32 v3, v3
	v_sub_f32_e32 v4, v23, v90
	v_exp_f32_e32 v22, v5
	v_sub_f32_e32 v5, v10, v90
	v_exp_f32_e32 v101, v4
	v_sub_f32_e32 v4, v7, v90
	v_exp_f32_e32 v10, v5
	v_sub_f32_e32 v5, v27, v90
	v_exp_f32_e32 v103, v4
	v_sub_f32_e32 v4, v24, v90
	v_exp_f32_e32 v24, v5
	v_sub_f32_e32 v5, v11, v90
	v_sub_f32_e32 v11, v13, v90
	v_sub_f32_e32 v0, v0, v90
	v_exp_f32_e32 v21, v11
	v_sub_f32_e32 v11, v30, v90
	v_exp_f32_e32 v0, v0
	v_exp_f32_e32 v1, v1
	v_sub_f32_e32 v9, v29, v90
	v_exp_f32_e32 v23, v11
	v_pk_mul_f32 v[2:3], v[90:91], v[2:3] op_sel:[1,0]
	v_sub_f32_e32 v7, v12, v90
	v_exp_f32_e32 v9, v9
	v_sub_f32_e32 v12, v31, v90
	v_pk_fma_f32 v[2:3], v[90:91], v[96:97], v[2:3] op_sel:[1,0,0]
	v_exp_f32_e32 v25, v12
	v_pk_fma_f32 v[2:3], v[90:91], v[102:103], v[2:3] op_sel:[1,0,0]
	v_exp_f32_e32 v26, v5
	v_sub_f32_e32 v5, v28, v90
	v_pk_add_f32 v[2:3], v[2:3], v[2:3]
	v_exp_f32_e32 v4, v4
	v_exp_f32_e32 v5, v5
	v_sub_f32_e32 v11, v14, v90
	v_pk_fma_f32 v[2:3], v[90:91], v[0:1], v[2:3] op_sel:[1,0,0]
	v_pk_fma_f32 v[70:71], v[90:91], v[0:1], v[70:71] op_sel:[1,0,0]
	v_pk_mul_f32 v[0:1], v[90:91], v[22:23] op_sel:[1,0]
	v_exp_f32_e32 v11, v11
	v_pk_fma_f32 v[0:1], v[90:91], v[8:9], v[0:1] op_sel:[1,0,0]
	v_sub_f32_e32 v12, v15, v90
	v_pk_fma_f32 v[0:1], v[90:91], v[24:25], v[0:1] op_sel:[1,0,0]
	v_exp_f32_e32 v27, v12
	v_pk_add_f32 v[0:1], v[0:1], v[0:1]
	v_sub_f32_e32 v16, v16, v90
	v_pk_fma_f32 v[0:1], v[90:91], v[4:5], v[0:1] op_sel:[1,0,0]
	v_exp_f32_e32 v16, v16
	v_exp_f32_e32 v7, v7
	v_pk_mul_f32 v[12:13], v[90:91], v[18:19] op_sel:[1,0]
	v_pk_add_f32 v[84:85], v[84:85], v[0:1]
	v_pk_mul_f32 v[0:1], v[90:91], v[10:11] op_sel:[1,0]
	v_pk_fma_f32 v[12:13], v[90:91], v[94:95], v[12:13] op_sel:[1,0,0]
	v_pk_fma_f32 v[0:1], v[90:91], v[20:21], v[0:1] op_sel:[1,0,0]
	v_pk_fma_f32 v[12:13], v[90:91], v[100:101], v[12:13] op_sel:[1,0,0]
	v_pk_fma_f32 v[0:1], v[90:91], v[26:27], v[0:1] op_sel:[1,0,0]
	v_pk_add_f32 v[12:13], v[12:13], v[12:13]
	v_pk_add_f32 v[0:1], v[0:1], v[0:1]
	v_pk_fma_f32 v[12:13], v[90:91], v[16:17], v[12:13] op_sel:[1,0,0]
	v_pk_fma_f32 v[0:1], v[90:91], v[6:7], v[0:1] op_sel:[1,0,0]
	s_addk_i32 s74, 0x100
	v_pk_add_f32 v[86:87], v[86:87], v[12:13]
	v_pk_fma_f32 v[74:75], v[90:91], v[16:17], v[74:75] op_sel:[1,0,0]
	v_pk_add_f32 v[78:79], v[78:79], v[2:3]
	v_pk_fma_f32 v[72:73], v[90:91], v[4:5], v[72:73] op_sel:[1,0,0]
	v_pk_add_f32 v[76:77], v[76:77], v[0:1]
	v_pk_fma_f32 v[68:69], v[90:91], v[6:7], v[68:69] op_sel:[1,0,0]
	s_branch .LBB0_775
